# P5: later items no longer wait for the q~ rows at the loop top (already covered by the previous step C's counted wait; the old wait stalled on output-store acks)
# baseline (speedup 1.0000x reference)
.Lp5c_w2:
	ds_write_b128 v107, v[22:25]
	ds_write_b128 v107, v[18:21] offset:8192
